# E9: E1 + .p2align 6 on the five hot loop heads (attention main loop, four GEMM K-loops)
# baseline (speedup 1.0000x reference)
.LBB0_183:
	s_ashr_i32 s57, s56, 31
	s_lshl_b64 s[40:41], s[56:57], 19
	s_add_u32 s58, s68, s40
	s_addc_u32 s59, s69, s41
	s_and_b64 s[40:41], s[38:39], exec
	s_cselect_b32 s57, s59, s29
	s_cselect_b32 s62, s58, s28
	s_ashr_i32 s55, s54, 31
	s_lshl_b64 s[40:41], s[54:55], 19
	s_add_u32 s60, s70, s40
	s_addc_u32 s61, s71, s41
	s_and_b64 s[40:41], s[38:39], exec
	s_cselect_b32 s55, s61, s25
	s_cselect_b32 s63, s60, s24
	s_add_u32 s28, s28, 0x40080
	s_addc_u32 s29, s29, 0
	s_add_u32 s64, s24, 0x100
	v_mov_b32_e32 v4, 0
	s_addc_u32 s65, s25, 0
	s_mov_b32 s66, -2
	v_mov_b32_e32 v5, v4
	v_mov_b32_e32 v6, v4
	v_mov_b32_e32 v7, v4
	v_mov_b32_e32 v8, v4
	v_mov_b32_e32 v9, v4
	v_mov_b32_e32 v10, v4
	v_mov_b32_e32 v11, v4
	v_mov_b32_e32 v20, v4
	v_mov_b32_e32 v21, v4
	v_mov_b32_e32 v22, v4
	v_mov_b32_e32 v23, v4
	v_mov_b32_e32 v24, v4
	v_mov_b32_e32 v25, v4
	v_mov_b32_e32 v26, v4
	v_mov_b32_e32 v27, v4
	v_mov_b32_e32 v36, v4
	v_mov_b32_e32 v37, v4
	v_mov_b32_e32 v38, v4
	v_mov_b32_e32 v39, v4
	v_mov_b32_e32 v40, v4
	v_mov_b32_e32 v41, v4
	v_mov_b32_e32 v42, v4
	v_mov_b32_e32 v43, v4
	v_mov_b32_e32 v52, v4
	v_mov_b32_e32 v53, v4
	v_mov_b32_e32 v54, v4
	v_mov_b32_e32 v55, v4
	v_mov_b32_e32 v56, v4
	v_mov_b32_e32 v57, v4
	v_mov_b32_e32 v58, v4
	v_mov_b32_e32 v59, v4
	v_mov_b32_e32 v12, v4
	v_mov_b32_e32 v13, v4
	v_mov_b32_e32 v14, v4
	v_mov_b32_e32 v15, v4
	v_mov_b32_e32 v16, v4
	v_mov_b32_e32 v17, v4
	v_mov_b32_e32 v18, v4
	v_mov_b32_e32 v19, v4
	v_mov_b32_e32 v28, v4
	v_mov_b32_e32 v29, v4
	v_mov_b32_e32 v30, v4
	v_mov_b32_e32 v31, v4
	v_mov_b32_e32 v32, v4
	v_mov_b32_e32 v33, v4
	v_mov_b32_e32 v34, v4
	v_mov_b32_e32 v35, v4
	v_mov_b32_e32 v44, v4
	v_mov_b32_e32 v45, v4
	v_mov_b32_e32 v46, v4
	v_mov_b32_e32 v47, v4
	v_mov_b32_e32 v48, v4
	v_mov_b32_e32 v49, v4
	v_mov_b32_e32 v50, v4
	v_mov_b32_e32 v51, v4
	v_mov_b32_e32 v60, v4
	v_mov_b32_e32 v61, v4
	v_mov_b32_e32 v62, v4
	v_mov_b32_e32 v63, v4
	v_mov_b32_e32 v64, v4
	v_mov_b32_e32 v65, v4
	v_mov_b32_e32 v66, v4
	v_mov_b32_e32 v67, v4
	v_mov_b32_e32 v68, v4
	v_mov_b32_e32 v69, v4
	v_mov_b32_e32 v70, v4
	v_mov_b32_e32 v71, v4
	v_mov_b32_e32 v72, v4
	v_mov_b32_e32 v73, v4
	v_mov_b32_e32 v74, v4
	v_mov_b32_e32 v75, v4
	v_mov_b32_e32 v84, v4
	v_mov_b32_e32 v85, v4
	v_mov_b32_e32 v86, v4
	v_mov_b32_e32 v87, v4
	v_mov_b32_e32 v88, v4
	v_mov_b32_e32 v89, v4
	v_mov_b32_e32 v90, v4
	v_mov_b32_e32 v91, v4
	s_waitcnt vmcnt(0)
	v_mov_b32_e32 v100, v4
	v_mov_b32_e32 v101, v4
	v_mov_b32_e32 v102, v4
	v_mov_b32_e32 v103, v4
	v_mov_b32_e32 v104, v4
	v_mov_b32_e32 v105, v4
	v_mov_b32_e32 v106, v4
	v_mov_b32_e32 v107, v4
	v_mov_b32_e32 v116, v4
	v_mov_b32_e32 v117, v4
	v_mov_b32_e32 v118, v4
	v_mov_b32_e32 v119, v4
	v_mov_b32_e32 v120, v4
	v_mov_b32_e32 v121, v4
	v_mov_b32_e32 v122, v4
	v_mov_b32_e32 v123, v4
	v_mov_b32_e32 v76, v4
	v_mov_b32_e32 v77, v4
	v_mov_b32_e32 v78, v4
	v_mov_b32_e32 v79, v4
	v_mov_b32_e32 v80, v4
	v_mov_b32_e32 v81, v4
	v_mov_b32_e32 v82, v4
	v_mov_b32_e32 v83, v4
	v_mov_b32_e32 v92, v4
	v_mov_b32_e32 v93, v4
	v_mov_b32_e32 v94, v4
	v_mov_b32_e32 v95, v4
	v_mov_b32_e32 v96, v4
	v_mov_b32_e32 v97, v4
	v_mov_b32_e32 v98, v4
	v_mov_b32_e32 v99, v4
	v_mov_b32_e32 v108, v4
	v_mov_b32_e32 v109, v4
	v_mov_b32_e32 v110, v4
	v_mov_b32_e32 v111, v4
	v_mov_b32_e32 v112, v4
	v_mov_b32_e32 v113, v4
	v_mov_b32_e32 v114, v4
	v_mov_b32_e32 v115, v4
	v_mov_b32_e32 v124, v4
	v_mov_b32_e32 v125, v4
	v_mov_b32_e32 v126, v4
	v_mov_b32_e32 v127, v4
	v_mov_b32_e32 v128, v4
	v_mov_b32_e32 v129, v4
	v_mov_b32_e32 v130, v4
	v_mov_b32_e32 v131, v4
	.p2align	6

.LBB0_730:
	s_lshl_b64 s[46:47], s[46:47], 1
	s_add_u32 s46, s54, s46
	s_addc_u32 s47, s55, s47
	s_add_u32 s46, s46, s28
	s_addc_u32 s47, s47, s29
	s_add_u32 s46, s46, s24
	s_addc_u32 s47, s47, s25
	s_lshl_b64 s[44:45], s[44:45], 1
	s_add_u32 s28, s44, s28
	s_addc_u32 s29, s45, s29
	v_exp_f32_e32 v52, v4
	v_and_b32_e32 v4, 3, v90
	s_add_u32 s24, s28, s24
	v_exp_f32_e32 v53, v5
	v_lshlrev_b32_e32 v4, 4, v4
	v_mov_b32_e32 v5, v2
	s_addc_u32 s25, s29, s25
	v_lshlrev_b32_e32 v0, 1, v90
	v_lshl_add_u64 v[4:5], s[24:25], 0, v[4:5]
	s_lshl_b32 s24, s60, 6
	v_exp_f32_e32 v68, v20
	v_exp_f32_e32 v69, v21
	v_exp_f32_e32 v70, v22
	v_exp_f32_e32 v71, v23
	v_exp_f32_e32 v72, v24
	v_exp_f32_e32 v73, v25
	v_exp_f32_e32 v74, v26
	v_exp_f32_e32 v75, v27
	v_exp_f32_e32 v76, v28
	v_exp_f32_e32 v77, v29
	v_exp_f32_e32 v78, v30
	v_exp_f32_e32 v79, v31
	v_exp_f32_e32 v80, v32
	v_exp_f32_e32 v81, v33
	v_exp_f32_e32 v82, v34
	v_exp_f32_e32 v83, v35
	v_exp_f32_e32 v54, v6
	v_exp_f32_e32 v55, v7
	v_exp_f32_e32 v56, v8
	v_exp_f32_e32 v57, v9
	v_exp_f32_e32 v58, v10
	v_exp_f32_e32 v59, v11
	v_exp_f32_e32 v60, v12
	v_exp_f32_e32 v61, v13
	v_exp_f32_e32 v62, v14
	v_exp_f32_e32 v63, v15
	v_exp_f32_e32 v64, v16
	v_exp_f32_e32 v65, v17
	v_exp_f32_e32 v66, v18
	v_exp_f32_e32 v67, v19
	v_and_b32_e32 v194, 32, v0
	v_lshlrev_b32_e32 v0, 4, v90
	s_and_b32 s24, s24, 0x3000
	v_and_b32_e32 v0, 0xc0, v0
	v_lshl_or_b32 v6, v91, 8, s24
	v_mov_b32_e32 v7, v2
	v_lshl_or_b32 v3, v189, 8, v0
	v_add_u32_e32 v0, 0, v194
	v_lshl_add_u64 v[4:5], v[4:5], 0, v[6:7]
	v_mov_b32_e32 v192, 0
	v_add3_u32 v190, v0, v193, v3
	v_lshl_add_u64 v[0:1], s[46:47], 0, v[88:89]
	v_lshl_add_u64 v[184:185], s[38:39], 0, v[4:5]
	s_movk_i32 s29, 0x4000
	s_movk_i32 s25, 0x2000
	s_mov_b32 s45, 0
	s_mov_b32 s24, -1
	v_mov_b32_e32 v4, 0
	v_mov_b32_e32 v5, v192
	v_mov_b32_e32 v6, v192
	v_mov_b32_e32 v7, v192
	v_mov_b32_e32 v8, v192
	v_mov_b32_e32 v9, v192
	v_mov_b32_e32 v10, v192
	v_mov_b32_e32 v11, v192
	v_mov_b32_e32 v12, v192
	v_mov_b32_e32 v13, v192
	v_mov_b32_e32 v14, v192
	v_mov_b32_e32 v15, v192
	v_mov_b32_e32 v16, v192
	v_mov_b32_e32 v17, v192
	v_mov_b32_e32 v18, v192
	v_mov_b32_e32 v19, v192
	v_mov_b32_e32 v20, 0
	v_mov_b32_e32 v21, v192
	v_mov_b32_e32 v22, v192
	v_mov_b32_e32 v23, v192
	v_mov_b32_e32 v24, v192
	v_mov_b32_e32 v25, v192
	v_mov_b32_e32 v26, v192
	v_mov_b32_e32 v27, v192
	v_mov_b32_e32 v28, v192
	v_mov_b32_e32 v29, v192
	v_mov_b32_e32 v30, v192
	v_mov_b32_e32 v31, v192
	v_mov_b32_e32 v32, v192
	v_mov_b32_e32 v33, v192
	v_mov_b32_e32 v34, v192
	v_mov_b32_e32 v35, v192
	.p2align	6

.LBB0_799:
	s_ashr_i32 s57, s56, 31
	s_lshl_b64 s[58:59], s[56:57], 19
	s_add_u32 s58, s3, s58
	s_addc_u32 s59, s68, s59
	s_and_b64 s[60:61], s[42:43], exec
	s_cselect_b32 s57, s59, s63
	s_cselect_b32 s92, s58, s62
	s_ashr_i32 s55, s54, 31
	s_lshl_b64 s[60:61], s[54:55], 19
	s_add_u32 s60, s69, s60
	s_addc_u32 s61, s70, s61
	s_and_b64 s[64:65], s[42:43], exec
	s_cselect_b32 s55, s61, s25
	s_cselect_b32 s93, s60, s24
	s_add_u32 s94, s24, 0x100
	v_mov_b32_e32 v4, 0
	s_addc_u32 s95, s25, 0
	s_mov_b32 s96, -2
	s_waitcnt lgkmcnt(0)
	v_mov_b32_e32 v5, v4
	v_mov_b32_e32 v6, v4
	v_mov_b32_e32 v7, v4
	v_mov_b32_e32 v8, v4
	v_mov_b32_e32 v9, v4
	v_mov_b32_e32 v10, v4
	v_mov_b32_e32 v11, v4
	v_mov_b32_e32 v20, v4
	v_mov_b32_e32 v21, v4
	v_mov_b32_e32 v22, v4
	v_mov_b32_e32 v23, v4
	v_mov_b32_e32 v24, v4
	v_mov_b32_e32 v25, v4
	v_mov_b32_e32 v26, v4
	v_mov_b32_e32 v27, v4
	v_mov_b32_e32 v36, v4
	v_mov_b32_e32 v37, v4
	v_mov_b32_e32 v38, v4
	v_mov_b32_e32 v39, v4
	v_mov_b32_e32 v40, v4
	v_mov_b32_e32 v41, v4
	v_mov_b32_e32 v42, v4
	v_mov_b32_e32 v43, v4
	v_mov_b32_e32 v52, v4
	v_mov_b32_e32 v53, v4
	v_mov_b32_e32 v54, v4
	v_mov_b32_e32 v55, v4
	v_mov_b32_e32 v56, v4
	v_mov_b32_e32 v57, v4
	v_mov_b32_e32 v58, v4
	v_mov_b32_e32 v59, v4
	v_mov_b32_e32 v12, v4
	v_mov_b32_e32 v13, v4
	v_mov_b32_e32 v14, v4
	v_mov_b32_e32 v15, v4
	v_mov_b32_e32 v16, v4
	v_mov_b32_e32 v17, v4
	v_mov_b32_e32 v18, v4
	v_mov_b32_e32 v19, v4
	v_mov_b32_e32 v28, v4
	v_mov_b32_e32 v29, v4
	v_mov_b32_e32 v30, v4
	v_mov_b32_e32 v31, v4
	v_mov_b32_e32 v32, v4
	v_mov_b32_e32 v33, v4
	v_mov_b32_e32 v34, v4
	v_mov_b32_e32 v35, v4
	v_mov_b32_e32 v44, v4
	v_mov_b32_e32 v45, v4
	v_mov_b32_e32 v46, v4
	v_mov_b32_e32 v47, v4
	v_mov_b32_e32 v48, v4
	v_mov_b32_e32 v49, v4
	v_mov_b32_e32 v50, v4
	v_mov_b32_e32 v51, v4
	v_mov_b32_e32 v60, v4
	v_mov_b32_e32 v61, v4
	v_mov_b32_e32 v62, v4
	v_mov_b32_e32 v63, v4
	v_mov_b32_e32 v64, v4
	v_mov_b32_e32 v65, v4
	v_mov_b32_e32 v66, v4
	v_mov_b32_e32 v67, v4
	v_mov_b32_e32 v68, v4
	v_mov_b32_e32 v69, v4
	v_mov_b32_e32 v70, v4
	v_mov_b32_e32 v71, v4
	v_mov_b32_e32 v72, v4
	v_mov_b32_e32 v73, v4
	v_mov_b32_e32 v74, v4
	v_mov_b32_e32 v75, v4
	v_mov_b32_e32 v84, v4
	v_mov_b32_e32 v85, v4
	v_mov_b32_e32 v86, v4
	v_mov_b32_e32 v87, v4
	v_mov_b32_e32 v88, v4
	v_mov_b32_e32 v89, v4
	v_mov_b32_e32 v90, v4
	v_mov_b32_e32 v91, v4
	s_waitcnt vmcnt(0)
	v_mov_b32_e32 v100, v4
	v_mov_b32_e32 v101, v4
	v_mov_b32_e32 v102, v4
	v_mov_b32_e32 v103, v4
	v_mov_b32_e32 v104, v4
	v_mov_b32_e32 v105, v4
	v_mov_b32_e32 v106, v4
	v_mov_b32_e32 v107, v4
	v_mov_b32_e32 v116, v4
	v_mov_b32_e32 v117, v4
	v_mov_b32_e32 v118, v4
	v_mov_b32_e32 v119, v4
	v_mov_b32_e32 v120, v4
	v_mov_b32_e32 v121, v4
	v_mov_b32_e32 v122, v4
	v_mov_b32_e32 v123, v4
	v_mov_b32_e32 v76, v4
	v_mov_b32_e32 v77, v4
	v_mov_b32_e32 v78, v4
	v_mov_b32_e32 v79, v4
	v_mov_b32_e32 v80, v4
	v_mov_b32_e32 v81, v4
	v_mov_b32_e32 v82, v4
	v_mov_b32_e32 v83, v4
	v_mov_b32_e32 v92, v4
	v_mov_b32_e32 v93, v4
	v_mov_b32_e32 v94, v4
	v_mov_b32_e32 v95, v4
	v_mov_b32_e32 v96, v4
	v_mov_b32_e32 v97, v4
	v_mov_b32_e32 v98, v4
	v_mov_b32_e32 v99, v4
	v_mov_b32_e32 v108, v4
	v_mov_b32_e32 v109, v4
	v_mov_b32_e32 v110, v4
	v_mov_b32_e32 v111, v4
	v_mov_b32_e32 v112, v4
	v_mov_b32_e32 v113, v4
	v_mov_b32_e32 v114, v4
	v_mov_b32_e32 v115, v4
	v_mov_b32_e32 v124, v4
	v_mov_b32_e32 v125, v4
	v_mov_b32_e32 v126, v4
	v_mov_b32_e32 v127, v4
	v_mov_b32_e32 v128, v4
	v_mov_b32_e32 v129, v4
	v_mov_b32_e32 v130, v4
	v_mov_b32_e32 v131, v4
	.p2align	6

.LBB0_888:
	s_ashr_i32 s53, s52, 31
	s_lshl_b64 s[54:55], s[52:53], 19
	s_add_u32 s54, s3, s54
	s_addc_u32 s55, s60, s55
	s_and_b64 s[56:57], s[40:41], exec
	s_cselect_b32 s53, s55, s29
	s_cselect_b32 s84, s54, s28
	s_ashr_i32 s51, s50, 31
	s_lshl_b64 s[56:57], s[50:51], 19
	s_add_u32 s56, s61, s56
	s_addc_u32 s57, s62, s57
	s_and_b64 s[58:59], s[40:41], exec
	s_cselect_b32 s51, s57, s25
	s_cselect_b32 s85, s56, s24
	s_add_u32 s28, s28, 0x40080
	s_addc_u32 s29, s29, 0
	s_add_u32 s86, s24, 0x100
	v_mov_b32_e32 v4, 0
	s_addc_u32 s87, s25, 0
	s_mov_b32 s88, -2
	v_mov_b32_e32 v5, v4
	v_mov_b32_e32 v6, v4
	v_mov_b32_e32 v7, v4
	v_mov_b32_e32 v8, v4
	v_mov_b32_e32 v9, v4
	v_mov_b32_e32 v10, v4
	v_mov_b32_e32 v11, v4
	v_mov_b32_e32 v20, v4
	v_mov_b32_e32 v21, v4
	v_mov_b32_e32 v22, v4
	v_mov_b32_e32 v23, v4
	v_mov_b32_e32 v24, v4
	v_mov_b32_e32 v25, v4
	v_mov_b32_e32 v26, v4
	v_mov_b32_e32 v27, v4
	v_mov_b32_e32 v36, v4
	v_mov_b32_e32 v37, v4
	v_mov_b32_e32 v38, v4
	v_mov_b32_e32 v39, v4
	v_mov_b32_e32 v40, v4
	v_mov_b32_e32 v41, v4
	v_mov_b32_e32 v42, v4
	v_mov_b32_e32 v43, v4
	v_mov_b32_e32 v52, v4
	v_mov_b32_e32 v53, v4
	v_mov_b32_e32 v54, v4
	v_mov_b32_e32 v55, v4
	v_mov_b32_e32 v56, v4
	v_mov_b32_e32 v57, v4
	v_mov_b32_e32 v58, v4
	v_mov_b32_e32 v59, v4
	v_mov_b32_e32 v12, v4
	v_mov_b32_e32 v13, v4
	v_mov_b32_e32 v14, v4
	v_mov_b32_e32 v15, v4
	v_mov_b32_e32 v16, v4
	v_mov_b32_e32 v17, v4
	v_mov_b32_e32 v18, v4
	v_mov_b32_e32 v19, v4
	v_mov_b32_e32 v28, v4
	v_mov_b32_e32 v29, v4
	v_mov_b32_e32 v30, v4
	v_mov_b32_e32 v31, v4
	v_mov_b32_e32 v32, v4
	v_mov_b32_e32 v33, v4
	v_mov_b32_e32 v34, v4
	v_mov_b32_e32 v35, v4
	v_mov_b32_e32 v44, v4
	v_mov_b32_e32 v45, v4
	v_mov_b32_e32 v46, v4
	v_mov_b32_e32 v47, v4
	v_mov_b32_e32 v48, v4
	v_mov_b32_e32 v49, v4
	v_mov_b32_e32 v50, v4
	v_mov_b32_e32 v51, v4
	v_mov_b32_e32 v60, v4
	v_mov_b32_e32 v61, v4
	v_mov_b32_e32 v62, v4
	v_mov_b32_e32 v63, v4
	v_mov_b32_e32 v64, v4
	v_mov_b32_e32 v65, v4
	v_mov_b32_e32 v66, v4
	v_mov_b32_e32 v67, v4
	v_mov_b32_e32 v68, v4
	v_mov_b32_e32 v69, v4
	v_mov_b32_e32 v70, v4
	v_mov_b32_e32 v71, v4
	v_mov_b32_e32 v72, v4
	v_mov_b32_e32 v73, v4
	v_mov_b32_e32 v74, v4
	v_mov_b32_e32 v75, v4
	v_mov_b32_e32 v84, v4
	v_mov_b32_e32 v85, v4
	v_mov_b32_e32 v86, v4
	v_mov_b32_e32 v87, v4
	v_mov_b32_e32 v88, v4
	v_mov_b32_e32 v89, v4
	v_mov_b32_e32 v90, v4
	v_mov_b32_e32 v91, v4
	s_waitcnt vmcnt(0)
	v_mov_b32_e32 v100, v4
	v_mov_b32_e32 v101, v4
	v_mov_b32_e32 v102, v4
	v_mov_b32_e32 v103, v4
	v_mov_b32_e32 v104, v4
	v_mov_b32_e32 v105, v4
	v_mov_b32_e32 v106, v4
	v_mov_b32_e32 v107, v4
	v_mov_b32_e32 v116, v4
	v_mov_b32_e32 v117, v4
	v_mov_b32_e32 v118, v4
	v_mov_b32_e32 v119, v4
	v_mov_b32_e32 v120, v4
	v_mov_b32_e32 v121, v4
	v_mov_b32_e32 v122, v4
	v_mov_b32_e32 v123, v4
	v_mov_b32_e32 v76, v4
	v_mov_b32_e32 v77, v4
	v_mov_b32_e32 v78, v4
	v_mov_b32_e32 v79, v4
	v_mov_b32_e32 v80, v4
	v_mov_b32_e32 v81, v4
	v_mov_b32_e32 v82, v4
	v_mov_b32_e32 v83, v4
	v_mov_b32_e32 v92, v4
	v_mov_b32_e32 v93, v4
	v_mov_b32_e32 v94, v4
	v_mov_b32_e32 v95, v4
	v_mov_b32_e32 v96, v4
	v_mov_b32_e32 v97, v4
	v_mov_b32_e32 v98, v4
	v_mov_b32_e32 v99, v4
	v_mov_b32_e32 v108, v4
	v_mov_b32_e32 v109, v4
	v_mov_b32_e32 v110, v4
	v_mov_b32_e32 v111, v4
	v_mov_b32_e32 v112, v4
	v_mov_b32_e32 v113, v4
	v_mov_b32_e32 v114, v4
	v_mov_b32_e32 v115, v4
	v_mov_b32_e32 v124, v4
	v_mov_b32_e32 v125, v4
	v_mov_b32_e32 v126, v4
	v_mov_b32_e32 v127, v4
	v_mov_b32_e32 v128, v4
	v_mov_b32_e32 v129, v4
	v_mov_b32_e32 v130, v4
	v_mov_b32_e32 v131, v4
	.p2align	6

.LBB0_960:
	s_ashr_i32 s55, s54, 31
	s_lshl_b64 s[56:57], s[54:55], 21
	s_add_u32 s56, s3, s56
	s_addc_u32 s57, s26, s57
	s_and_b64 s[58:59], s[40:41], exec
	s_cselect_b32 s55, s57, s29
	s_cselect_b32 s88, s56, s28
	s_ashr_i32 s53, s52, 31
	s_lshl_b64 s[58:59], s[52:53], 21
	s_add_u32 s58, s64, s58
	s_addc_u32 s59, s65, s59
	s_and_b64 s[60:61], s[40:41], exec
	s_cselect_b32 s53, s59, s25
	s_cselect_b32 s89, s58, s24
	s_add_u32 s90, s24, 0x100
	v_mov_b32_e32 v4, 0
	s_addc_u32 s91, s25, 0
	s_mov_b32 s92, -2
	s_waitcnt lgkmcnt(0)
	v_mov_b32_e32 v5, v4
	v_mov_b32_e32 v6, v4
	v_mov_b32_e32 v7, v4
	v_mov_b32_e32 v8, v4
	v_mov_b32_e32 v9, v4
	v_mov_b32_e32 v10, v4
	v_mov_b32_e32 v11, v4
	v_mov_b32_e32 v20, v4
	v_mov_b32_e32 v21, v4
	v_mov_b32_e32 v22, v4
	v_mov_b32_e32 v23, v4
	v_mov_b32_e32 v24, v4
	v_mov_b32_e32 v25, v4
	v_mov_b32_e32 v26, v4
	v_mov_b32_e32 v27, v4
	v_mov_b32_e32 v36, v4
	v_mov_b32_e32 v37, v4
	v_mov_b32_e32 v38, v4
	v_mov_b32_e32 v39, v4
	v_mov_b32_e32 v40, v4
	v_mov_b32_e32 v41, v4
	v_mov_b32_e32 v42, v4
	v_mov_b32_e32 v43, v4
	v_mov_b32_e32 v52, v4
	v_mov_b32_e32 v53, v4
	v_mov_b32_e32 v54, v4
	v_mov_b32_e32 v55, v4
	v_mov_b32_e32 v56, v4
	v_mov_b32_e32 v57, v4
	v_mov_b32_e32 v58, v4
	v_mov_b32_e32 v59, v4
	v_mov_b32_e32 v12, v4
	v_mov_b32_e32 v13, v4
	v_mov_b32_e32 v14, v4
	v_mov_b32_e32 v15, v4
	v_mov_b32_e32 v16, v4
	v_mov_b32_e32 v17, v4
	v_mov_b32_e32 v18, v4
	v_mov_b32_e32 v19, v4
	v_mov_b32_e32 v28, v4
	v_mov_b32_e32 v29, v4
	v_mov_b32_e32 v30, v4
	v_mov_b32_e32 v31, v4
	v_mov_b32_e32 v32, v4
	v_mov_b32_e32 v33, v4
	v_mov_b32_e32 v34, v4
	v_mov_b32_e32 v35, v4
	v_mov_b32_e32 v44, v4
	v_mov_b32_e32 v45, v4
	v_mov_b32_e32 v46, v4
	v_mov_b32_e32 v47, v4
	v_mov_b32_e32 v48, v4
	v_mov_b32_e32 v49, v4
	v_mov_b32_e32 v50, v4
	v_mov_b32_e32 v51, v4
	v_mov_b32_e32 v60, v4
	v_mov_b32_e32 v61, v4
	v_mov_b32_e32 v62, v4
	v_mov_b32_e32 v63, v4
	v_mov_b32_e32 v64, v4
	v_mov_b32_e32 v65, v4
	v_mov_b32_e32 v66, v4
	v_mov_b32_e32 v67, v4
	v_mov_b32_e32 v68, v4
	v_mov_b32_e32 v69, v4
	v_mov_b32_e32 v70, v4
	v_mov_b32_e32 v71, v4
	v_mov_b32_e32 v72, v4
	v_mov_b32_e32 v73, v4
	v_mov_b32_e32 v74, v4
	v_mov_b32_e32 v75, v4
	v_mov_b32_e32 v84, v4
	v_mov_b32_e32 v85, v4
	v_mov_b32_e32 v86, v4
	v_mov_b32_e32 v87, v4
	v_mov_b32_e32 v88, v4
	v_mov_b32_e32 v89, v4
	v_mov_b32_e32 v90, v4
	v_mov_b32_e32 v91, v4
	s_waitcnt vmcnt(0)
	v_mov_b32_e32 v100, v4
	v_mov_b32_e32 v101, v4
	v_mov_b32_e32 v102, v4
	v_mov_b32_e32 v103, v4
	v_mov_b32_e32 v104, v4
	v_mov_b32_e32 v105, v4
	v_mov_b32_e32 v106, v4
	v_mov_b32_e32 v107, v4
	v_mov_b32_e32 v116, v4
	v_mov_b32_e32 v117, v4
	v_mov_b32_e32 v118, v4
	v_mov_b32_e32 v119, v4
	v_mov_b32_e32 v120, v4
	v_mov_b32_e32 v121, v4
	v_mov_b32_e32 v122, v4
	v_mov_b32_e32 v123, v4
	v_mov_b32_e32 v76, v4
	v_mov_b32_e32 v77, v4
	v_mov_b32_e32 v78, v4
	v_mov_b32_e32 v79, v4
	v_mov_b32_e32 v80, v4
	v_mov_b32_e32 v81, v4
	v_mov_b32_e32 v82, v4
	v_mov_b32_e32 v83, v4
	v_mov_b32_e32 v92, v4
	v_mov_b32_e32 v93, v4
	v_mov_b32_e32 v94, v4
	v_mov_b32_e32 v95, v4
	v_mov_b32_e32 v96, v4
	v_mov_b32_e32 v97, v4
	v_mov_b32_e32 v98, v4
	v_mov_b32_e32 v99, v4
	v_mov_b32_e32 v108, v4
	v_mov_b32_e32 v109, v4
	v_mov_b32_e32 v110, v4
	v_mov_b32_e32 v111, v4
	v_mov_b32_e32 v112, v4
	v_mov_b32_e32 v113, v4
	v_mov_b32_e32 v114, v4
	v_mov_b32_e32 v115, v4
	v_mov_b32_e32 v124, v4
	v_mov_b32_e32 v125, v4
	v_mov_b32_e32 v126, v4
	v_mov_b32_e32 v127, v4
	v_mov_b32_e32 v128, v4
	v_mov_b32_e32 v129, v4
	v_mov_b32_e32 v130, v4
	v_mov_b32_e32 v131, v4
	.p2align	6
